# full stack on v16: + SB QK/PV LDS-read pipelining + uq/ukv pre-hook at epilogue head + peeled first K trip (no accumulator zeroing) + hoisted g_final in final pass + MLA loop-edge trims
# speedup vs baseline: 1.0018x; 1.0005x over previous
.LBB0_915:
	s_cmp_lt_i32 s16, 0
	s_cselect_b64 s[18:19], -1, 0
	s_or_b64 s[18:19], s[0:1], s[18:19]
	s_cmp_gt_i32 s31, s33
	s_cselect_b64 s[44:45], -1, 0
	s_or_b64 s[18:19], s[18:19], s[44:45]
	s_and_b64 vcc, exec, s[18:19]
	s_cbranch_vccnz .LBB0_921
	s_add_i32 s0, s31, 63
	s_cmp_lt_i32 s0, s8
	v_add_u32_e32 v213, v145, v143
	v_xad_u32 v214, v143, 32, v145
	v_xad_u32 v215, v143, 64, v145
	ds_read_b128 v[146:149], v213 offset:32768
	ds_read_b128 v[150:153], v213 offset:40960
	ds_read_b128 v[224:227], v214 offset:32768
	ds_read_b128 v[228:231], v214 offset:40960
	ds_read_b128 v[232:235], v215 offset:32768
	s_waitcnt lgkmcnt(4)
	v_mfma_f32_32x32x16_bf16 v[82:97], v[146:149], v[4:7], 0
	ds_read_b128 v[146:149], v215 offset:40960
	v_xad_u32 v216, v143, s56, v145
	s_waitcnt lgkmcnt(4)
	v_mfma_f32_32x32x16_bf16 v[98:113], v[150:153], v[4:7], 0
	ds_read_b128 v[150:153], v216 offset:32768
	s_waitcnt lgkmcnt(4)
	v_mfma_f32_32x32x16_bf16 v[82:97], v[224:227], v[8:11], v[82:97]
	ds_read_b128 v[224:227], v216 offset:40960
	v_xad_u32 v213, v143, s90, v145
	s_waitcnt lgkmcnt(4)
	v_mfma_f32_32x32x16_bf16 v[98:113], v[228:231], v[8:11], v[98:113]
	ds_read_b128 v[228:231], v213 offset:32768
	s_waitcnt lgkmcnt(4)
	v_mfma_f32_32x32x16_bf16 v[82:97], v[232:235], v[12:15], v[82:97]
	ds_read_b128 v[232:235], v213 offset:40960
	v_xad_u32 v214, v143, s91, v145
	s_waitcnt lgkmcnt(4)
	v_mfma_f32_32x32x16_bf16 v[98:113], v[146:149], v[12:15], v[98:113]
	ds_read_b128 v[146:149], v214 offset:32768
	s_waitcnt lgkmcnt(4)
	v_mfma_f32_32x32x16_bf16 v[82:97], v[150:153], v[114:117], v[82:97]
	ds_read_b128 v[150:153], v214 offset:40960
	v_xad_u32 v215, v143, s57, v145
	s_waitcnt lgkmcnt(4)
	v_mfma_f32_32x32x16_bf16 v[98:113], v[224:227], v[114:117], v[98:113]
	ds_read_b128 v[224:227], v215 offset:32768
	s_waitcnt lgkmcnt(4)
	v_mfma_f32_32x32x16_bf16 v[82:97], v[228:231], v[118:121], v[82:97]
	ds_read_b128 v[228:231], v215 offset:40960
	v_xad_u32 v216, v143, s28, v145
	s_waitcnt lgkmcnt(4)
	v_mfma_f32_32x32x16_bf16 v[98:113], v[232:235], v[118:121], v[98:113]
	ds_read_b128 v[232:235], v216 offset:32768
	s_waitcnt lgkmcnt(4)
	v_mfma_f32_32x32x16_bf16 v[82:97], v[146:149], v[122:125], v[82:97]
	ds_read_b128 v[146:149], v216 offset:40960
	s_waitcnt lgkmcnt(4)
	v_mfma_f32_32x32x16_bf16 v[98:113], v[150:153], v[122:125], v[98:113]
	s_waitcnt lgkmcnt(3)
	v_mfma_f32_32x32x16_bf16 v[82:97], v[224:227], v[126:129], v[82:97]
	s_waitcnt lgkmcnt(2)
	v_mfma_f32_32x32x16_bf16 v[98:113], v[228:231], v[126:129], v[98:113]
	s_waitcnt lgkmcnt(1)
	v_mfma_f32_32x32x16_bf16 v[82:97], v[232:235], v[130:133], v[82:97]
	s_waitcnt lgkmcnt(0)
	v_mfma_f32_32x32x16_bf16 v[98:113], v[146:149], v[130:133], v[98:113]
	ds_read_b64_tr_b16 v[236:237], v141 offset:0x0
	ds_read_b64_tr_b16 v[238:239], v141 offset:0x800
	ds_read_b64_tr_b16 v[240:241], v141 offset:0x1000
	ds_read_b64_tr_b16 v[242:243], v141 offset:0x1800
	ds_read_b64_tr_b16 v[244:245], v141 offset:0x2000
	ds_read_b64_tr_b16 v[246:247], v141 offset:0x2800
	ds_read_b64_tr_b16 v[248:249], v141 offset:0x3000
	ds_read_b64_tr_b16 v[250:251], v141 offset:0x3800
	s_nop 2
	v_min_f32_e32 v213, 0x42fc0000, v82
	v_min_f32_e32 v214, 0x42fc0000, v83
	v_min_f32_e32 v215, 0x42fc0000, v98
	v_min_f32_e32 v216, 0x42fc0000, v99
	v_exp_f32_e32 v162, v213
	v_exp_f32_e32 v163, v214
	v_exp_f32_e32 v164, v215
	v_exp_f32_e32 v165, v216
	v_min_f32_e32 v217, 0x42fc0000, v84
	v_min_f32_e32 v218, 0x42fc0000, v100
	v_min_f32_e32 v219, 0x42fc0000, v85
	v_min_f32_e32 v220, 0x42fc0000, v101
	v_exp_f32_e32 v166, v217
	v_exp_f32_e32 v180, v218
	v_exp_f32_e32 v167, v219
	v_exp_f32_e32 v181, v220
	v_min_f32_e32 v213, 0x42fc0000, v86
	v_min_f32_e32 v214, 0x42fc0000, v102
	v_min_f32_e32 v215, 0x42fc0000, v87
	v_min_f32_e32 v216, 0x42fc0000, v103
	v_exp_f32_e32 v148, v213
	v_exp_f32_e32 v170, v214
	v_exp_f32_e32 v149, v215
	v_exp_f32_e32 v171, v216
	v_min_f32_e32 v217, 0x42fc0000, v88
	v_min_f32_e32 v218, 0x42fc0000, v104
	v_min_f32_e32 v219, 0x42fc0000, v89
	v_min_f32_e32 v220, 0x42fc0000, v105
	v_exp_f32_e32 v168, v217
	v_exp_f32_e32 v182, v218
	v_exp_f32_e32 v169, v219
	v_exp_f32_e32 v183, v220
	v_min_f32_e32 v213, 0x42fc0000, v90
	v_min_f32_e32 v214, 0x42fc0000, v106
	v_min_f32_e32 v215, 0x42fc0000, v91
	v_min_f32_e32 v216, 0x42fc0000, v107
	v_exp_f32_e32 v150, v213
	v_exp_f32_e32 v172, v214
	v_exp_f32_e32 v151, v215
	v_exp_f32_e32 v173, v216
	v_min_f32_e32 v217, 0x42fc0000, v92
	v_min_f32_e32 v218, 0x42fc0000, v108
	v_min_f32_e32 v219, 0x42fc0000, v93
	v_min_f32_e32 v220, 0x42fc0000, v109
	v_exp_f32_e32 v106, v217
	v_exp_f32_e32 v184, v218
	v_exp_f32_e32 v107, v219
	v_exp_f32_e32 v185, v220
	v_min_f32_e32 v213, 0x42fc0000, v94
	v_min_f32_e32 v214, 0x42fc0000, v110
	v_min_f32_e32 v215, 0x42fc0000, v95
	v_min_f32_e32 v216, 0x42fc0000, v111
	v_exp_f32_e32 v108, v213
	v_exp_f32_e32 v176, v214
	v_exp_f32_e32 v109, v215
	v_exp_f32_e32 v177, v216
	v_min_f32_e32 v217, 0x42fc0000, v96
	v_min_f32_e32 v218, 0x42fc0000, v112
	v_min_f32_e32 v219, 0x42fc0000, v97
	v_min_f32_e32 v220, 0x42fc0000, v113
	v_exp_f32_e32 v110, v217
	v_exp_f32_e32 v174, v218
	v_exp_f32_e32 v111, v219
	v_exp_f32_e32 v175, v220
	v_add_f32_e32 v83, 1.0, v164
	v_add_f32_e32 v84, 1.0, v165
	v_add_f32_e32 v85, 1.0, v180
	v_add_f32_e32 v86, 1.0, v181
	v_add_f32_e32 v87, 1.0, v170
	v_add_f32_e32 v88, 1.0, v171
	v_add_f32_e32 v89, 1.0, v182
	v_add_f32_e32 v92, 1.0, v183
	v_add_f32_e32 v93, 1.0, v172
	v_add_f32_e32 v96, 1.0, v173
	v_add_f32_e32 v97, 1.0, v184
	v_add_f32_e32 v100, 1.0, v185
	v_add_f32_e32 v101, 1.0, v176
	v_add_f32_e32 v104, 1.0, v177
	v_add_f32_e32 v112, 1.0, v174
	v_add_f32_e32 v82, 1.0, v162
	v_rcp_f32_e32 v90, v83
	v_add_f32_e32 v83, 1.0, v163
	v_rcp_f32_e32 v91, v84
	v_add_f32_e32 v84, 1.0, v166
	v_rcp_f32_e32 v94, v85
	v_add_f32_e32 v85, 1.0, v167
	v_rcp_f32_e32 v95, v86
	v_add_f32_e32 v86, 1.0, v148
	v_rcp_f32_e32 v98, v87
	v_add_f32_e32 v87, 1.0, v149
	v_rcp_f32_e32 v99, v88
	v_add_f32_e32 v88, 1.0, v168
	v_rcp_f32_e32 v102, v89
	v_add_f32_e32 v89, 1.0, v169
	v_rcp_f32_e32 v103, v92
	v_add_f32_e32 v92, 1.0, v150
	v_rcp_f32_e32 v146, v93
	v_add_f32_e32 v93, 1.0, v151
	v_rcp_f32_e32 v147, v96
	v_add_f32_e32 v96, 1.0, v106
	v_rcp_f32_e32 v156, v97
	v_add_f32_e32 v97, 1.0, v107
	v_rcp_f32_e32 v157, v100
	v_add_f32_e32 v100, 1.0, v108
	v_rcp_f32_e32 v158, v101
	v_add_f32_e32 v101, 1.0, v109
	v_rcp_f32_e32 v159, v104
	v_add_f32_e32 v104, 1.0, v110
	v_add_f32_e32 v105, 1.0, v111
	v_rcp_f32_e32 v160, v112
	v_add_f32_e32 v112, 1.0, v175
	v_rcp_f32_e32 v82, v82
	v_rcp_f32_e32 v83, v83
	v_rcp_f32_e32 v84, v84
	v_rcp_f32_e32 v85, v85
	v_rcp_f32_e32 v86, v86
	v_rcp_f32_e32 v87, v87
	v_rcp_f32_e32 v88, v88
	v_rcp_f32_e32 v89, v89
	v_rcp_f32_e32 v92, v92
	v_rcp_f32_e32 v93, v93
	v_rcp_f32_e32 v96, v96
	v_rcp_f32_e32 v97, v97
	v_rcp_f32_e32 v100, v100
	v_rcp_f32_e32 v101, v101
	v_rcp_f32_e32 v104, v104
	v_rcp_f32_e32 v105, v105
	v_rcp_f32_e32 v161, v112
	v_pk_mul_f32 v[154:155], v[108:109], v[100:101]
	v_pk_mul_f32 v[112:113], v[106:107], v[96:97]
	v_pk_mul_f32 v[152:153], v[110:111], v[104:105]
	v_pk_mul_f32 v[150:151], v[150:151], v[92:93]
	v_pk_mul_f32 v[110:111], v[168:169], v[88:89]
	v_pk_mul_f32 v[148:149], v[148:149], v[86:87]
	v_pk_mul_f32 v[106:107], v[166:167], v[84:85]
	v_pk_mul_f32 v[108:109], v[162:163], v[82:83]
	v_pk_mul_f32 v[174:175], v[174:175], v[160:161]
	v_pk_mul_f32 v[176:177], v[176:177], v[158:159]
	v_pk_mul_f32 v[168:169], v[184:185], v[156:157]
	v_pk_mul_f32 v[172:173], v[172:173], v[146:147]
	v_pk_mul_f32 v[166:167], v[182:183], v[102:103]
	v_pk_mul_f32 v[170:171], v[170:171], v[98:99]
	v_pk_mul_f32 v[162:163], v[180:181], v[94:95]
	v_pk_mul_f32 v[164:165], v[164:165], v[90:91]
	s_cbranch_scc1 .LBB0_920
	v_add_u32_e32 v180, 0x4000003b, v192
	s_brev_b32 s0, -4
	v_cmp_lt_u32_e32 vcc, s0, v180
	v_add_u32_e32 v180, 27, v192
	v_cmp_gt_u32_e64 s[0:1], -2.0, v180
	v_add_u32_e32 v180, 58, v192
	v_cmp_gt_u32_e64 s[44:45], -2.0, v180
	v_add_u32_e32 v180, 26, v192
	v_cndmask_b32_e64 v90, v90, 0, s[0:1]
	v_cndmask_b32_e64 v164, v164, 1.0, s[0:1]
	v_cmp_gt_u32_e64 s[0:1], -2.0, v180
	v_add_u32_e32 v180, 57, v192
	v_cmp_gt_u32_e64 s[46:47], -2.0, v180
	v_add_u32_e32 v180, 25, v192
	v_cndmask_b32_e64 v91, v91, 0, s[0:1]
	v_cndmask_b32_e64 v165, v165, 1.0, s[0:1]
	v_cmp_gt_u32_e64 s[0:1], -2.0, v180
	v_add_u32_e32 v180, 56, v192
	v_cmp_gt_u32_e64 s[48:49], -2.0, v180
	v_add_u32_e32 v180, 24, v192
	v_cndmask_b32_e64 v94, v94, 0, s[0:1]
	v_cndmask_b32_e64 v162, v162, 1.0, s[0:1]
	v_cmp_gt_u32_e64 s[0:1], -2.0, v180
	v_add_u32_e32 v180, 51, v192
	v_cmp_gt_u32_e64 s[50:51], -2.0, v180
	v_add_u32_e32 v180, 19, v192
	v_cndmask_b32_e64 v95, v95, 0, s[0:1]
	v_cndmask_b32_e64 v163, v163, 1.0, s[0:1]
	v_cmp_gt_u32_e64 s[0:1], -2.0, v180
	v_add_u32_e32 v180, 50, v192
	v_cmp_gt_u32_e64 s[52:53], -2.0, v180
	v_add_u32_e32 v180, 18, v192
	v_cndmask_b32_e64 v98, v98, 0, s[0:1]
	v_cndmask_b32_e64 v170, v170, 1.0, s[0:1]
	v_cmp_gt_u32_e64 s[0:1], -2.0, v180
	v_add_u32_e32 v180, 49, v192
	v_cmp_gt_u32_e64 s[54:55], -2.0, v180
	v_add_u32_e32 v180, 17, v192
	v_cndmask_b32_e64 v99, v99, 0, s[0:1]
	v_cndmask_b32_e64 v171, v171, 1.0, s[0:1]
	v_cmp_gt_u32_e64 s[0:1], -2.0, v180
	v_add_u32_e32 v180, 48, v192
	v_cmp_gt_u32_e64 s[76:77], -2.0, v192
	v_cndmask_b32_e64 v102, v102, 0, s[0:1]
	v_cndmask_b32_e64 v166, v166, 1.0, s[0:1]
	v_cmp_gt_u32_e64 s[0:1], -2.0, v180
	v_add_u32_e32 v180, 16, v192
	v_cmp_gt_u32_e64 s[58:59], -2.0, v180
	v_add_u32_e32 v180, 43, v192
	s_nop 0
	v_cndmask_b32_e64 v103, v103, 0, s[58:59]
	v_cndmask_b32_e64 v167, v167, 1.0, s[58:59]
	v_cmp_gt_u32_e64 s[58:59], -2.0, v180
	v_add_u32_e32 v180, 11, v192
	v_cmp_gt_u32_e64 s[60:61], -2.0, v180
	v_add_u32_e32 v180, 42, v192
	s_nop 0
	v_cndmask_b32_e64 v146, v146, 0, s[60:61]
	v_cndmask_b32_e64 v172, v172, 1.0, s[60:61]
	v_cmp_gt_u32_e64 s[60:61], -2.0, v180
	v_add_u32_e32 v180, 10, v192
	v_cmp_gt_u32_e64 s[62:63], -2.0, v180
	v_add_u32_e32 v180, 41, v192
	s_nop 0
	v_cndmask_b32_e64 v147, v147, 0, s[62:63]
	v_cndmask_b32_e64 v173, v173, 1.0, s[62:63]
	v_cmp_gt_u32_e64 s[62:63], -2.0, v180
	v_add_u32_e32 v180, 9, v192
	v_cmp_gt_u32_e64 s[64:65], -2.0, v180
	v_add_u32_e32 v180, 40, v192
	s_nop 0
	v_cndmask_b32_e64 v156, v156, 0, s[64:65]
	v_cndmask_b32_e64 v168, v168, 1.0, s[64:65]
	v_cmp_gt_u32_e64 s[64:65], -2.0, v180
	v_add_u32_e32 v180, 8, v192
	v_cmp_gt_u32_e64 s[66:67], -2.0, v180
	v_add_u32_e32 v180, 35, v192
	s_nop 0
	v_cndmask_b32_e64 v157, v157, 0, s[66:67]
	v_cndmask_b32_e64 v169, v169, 1.0, s[66:67]
	v_cmp_gt_u32_e64 s[66:67], -2.0, v180
	v_add_u32_e32 v180, 3, v192
	v_cmp_gt_u32_e64 s[68:69], -2.0, v180
	v_add_u32_e32 v180, 34, v192
	s_nop 0
	v_cndmask_b32_e64 v158, v158, 0, s[68:69]
	v_cndmask_b32_e64 v176, v176, 1.0, s[68:69]
	v_cmp_gt_u32_e64 s[68:69], -2.0, v180
	v_add_u32_e32 v180, 2, v192
	v_cmp_gt_u32_e64 s[70:71], -2.0, v180
	v_add_u32_e32 v180, 33, v192
	s_nop 0
	v_cndmask_b32_e64 v159, v159, 0, s[70:71]
	v_cndmask_b32_e64 v177, v177, 1.0, s[70:71]
	v_cmp_gt_u32_e64 s[70:71], -2.0, v180
	v_add_u32_e32 v180, 1, v192
	v_cmp_gt_u32_e64 s[72:73], -2.0, v180
	v_add_u32_e32 v180, 32, v192
	s_nop 0
	v_cndmask_b32_e64 v160, v160, 0, s[72:73]
	v_cndmask_b32_e64 v174, v174, 1.0, s[72:73]
	v_cmp_gt_u32_e64 s[72:73], -2.0, v180
	s_and_saveexec_b64 s[18:19], s[76:77]
	s_mov_b32 s25, 1.0
	v_mov_b32_e32 v175, s25
	v_mov_b32_e32 v161, 0
	s_or_b64 exec, exec, s[18:19]
	v_cndmask_b32_e64 v82, v82, 0, vcc
	v_cndmask_b32_e64 v108, v108, 1.0, vcc
	v_cndmask_b32_e64 v83, v83, 0, s[44:45]
	v_cndmask_b32_e64 v109, v109, 1.0, s[44:45]
	v_cndmask_b32_e64 v84, v84, 0, s[46:47]
	v_cndmask_b32_e64 v106, v106, 1.0, s[46:47]
	v_cndmask_b32_e64 v85, v85, 0, s[48:49]
	v_cndmask_b32_e64 v107, v107, 1.0, s[48:49]
	v_cndmask_b32_e64 v86, v86, 0, s[50:51]
	v_cndmask_b32_e64 v148, v148, 1.0, s[50:51]
	v_cndmask_b32_e64 v87, v87, 0, s[52:53]
	v_cndmask_b32_e64 v149, v149, 1.0, s[52:53]
	v_cndmask_b32_e64 v88, v88, 0, s[54:55]
	v_cndmask_b32_e64 v110, v110, 1.0, s[54:55]
	v_cndmask_b32_e64 v89, v89, 0, s[0:1]
	v_cndmask_b32_e64 v111, v111, 1.0, s[0:1]
	v_cndmask_b32_e64 v92, v92, 0, s[58:59]
	v_cndmask_b32_e64 v150, v150, 1.0, s[58:59]
	v_cndmask_b32_e64 v93, v93, 0, s[60:61]
	v_cndmask_b32_e64 v151, v151, 1.0, s[60:61]
	v_cndmask_b32_e64 v96, v96, 0, s[62:63]
	v_cndmask_b32_e64 v112, v112, 1.0, s[62:63]
	v_cndmask_b32_e64 v97, v97, 0, s[64:65]
	v_cndmask_b32_e64 v113, v113, 1.0, s[64:65]
	v_cndmask_b32_e64 v100, v100, 0, s[66:67]
	v_cndmask_b32_e64 v154, v154, 1.0, s[66:67]
	v_cndmask_b32_e64 v101, v101, 0, s[68:69]
	v_cndmask_b32_e64 v155, v155, 1.0, s[68:69]
	v_cndmask_b32_e64 v104, v104, 0, s[70:71]
	v_cndmask_b32_e64 v152, v152, 1.0, s[70:71]
	v_cndmask_b32_e64 v105, v105, 0, s[72:73]
	v_cndmask_b32_e64 v153, v153, 1.0, s[72:73]
	v_readlane_b32 s48, v254, 46
.LBB0_920:
	v_mov_b32_e32 v184, v149
	v_mov_b32_e32 v185, v110
	v_mov_b32_e32 v194, v148
	v_mov_b32_e32 v195, v111
	v_pk_mul_f32 v[184:185], v[184:185], v[194:195]
	v_mov_b32_e32 v180, v109
	v_mov_b32_e32 v181, v106
	v_mov_b32_e32 v182, v108
	v_mov_b32_e32 v183, v107
	v_pk_mul_f32 v[184:185], v[184:185], v[184:185] op_sel:[0,1] op_sel_hi:[1,0]
	v_pk_mul_f32 v[180:181], v[180:181], v[182:183]
	v_mov_b32_e32 v108, v184
	v_mov_b32_e32 v196, v155
	v_mov_b32_e32 v197, v152
	v_mov_b32_e32 v198, v154
	v_mov_b32_e32 v199, v153
	v_pk_mul_f32 v[180:181], v[180:181], v[180:181] op_sel:[0,1] op_sel_hi:[1,0]
	v_permlane32_swap_b32_e32 v184, v108
	v_pk_mul_f32 v[196:197], v[196:197], v[198:199]
	v_mul_f32_e32 v181, v184, v108
	v_mov_b32_e32 v184, v151
	v_mov_b32_e32 v185, v112
	v_mov_b32_e32 v194, v150
	v_mov_b32_e32 v195, v113
	v_pk_mul_f32 v[196:197], v[196:197], v[196:197] op_sel:[0,1] op_sel_hi:[1,0]
	v_pk_mul_f32 v[184:185], v[184:185], v[194:195]
	v_mov_b32_e32 v148, v196
	v_mov_b32_e32 v200, v171
	v_mov_b32_e32 v201, v166
	v_mov_b32_e32 v202, v170
	v_mov_b32_e32 v203, v167
	v_pk_mul_f32 v[184:185], v[184:185], v[184:185] op_sel:[0,1] op_sel_hi:[1,0]
	v_permlane32_swap_b32_e32 v196, v148
	v_pk_mul_f32 v[200:201], v[200:201], v[202:203]
	v_mov_b32_e32 v204, v177
	v_mov_b32_e32 v205, v174
	v_mov_b32_e32 v206, v176
	v_mov_b32_e32 v207, v175
	v_mul_f32_e32 v185, v196, v148
	v_mov_b32_e32 v196, v165
	v_mov_b32_e32 v197, v162
	v_mov_b32_e32 v198, v164
	v_mov_b32_e32 v199, v163
	v_pk_mul_f32 v[200:201], v[200:201], v[200:201] op_sel:[0,1] op_sel_hi:[1,0]
	v_pk_mul_f32 v[204:205], v[204:205], v[206:207]
	v_pk_mul_f32 v[196:197], v[196:197], v[198:199]
	v_mov_b32_e32 v150, v200
	v_pk_mul_f32 v[204:205], v[204:205], v[204:205] op_sel:[0,1] op_sel_hi:[1,0]
	v_pk_mul_f32 v[196:197], v[196:197], v[196:197] op_sel:[0,1] op_sel_hi:[1,0]
	v_permlane32_swap_b32_e32 v200, v150
	v_mov_b32_e32 v154, v204
	v_mul_f32_e32 v197, v200, v150
	v_mov_b32_e32 v200, v173
	v_mov_b32_e32 v201, v168
	v_mov_b32_e32 v202, v172
	v_mov_b32_e32 v203, v169
	v_permlane32_swap_b32_e32 v204, v154
	v_pk_mul_f32 v[200:201], v[200:201], v[202:203]
	v_mul_f32_e32 v203, v204, v154
	v_cndmask_b32_e64 v154, 1.0, v154, s[38:39]
	v_mul_f32_e32 v154, v193, v154
	v_pk_mul_f32 v[200:201], v[200:201], v[200:201] op_sel:[0,1] op_sel_hi:[1,0]
	v_mul_f32_e32 v164, v175, v154
	v_mov_b32_e32 v202, v200
	v_mul_f32_e32 v170, v174, v164
	s_nop 0
	v_permlane32_swap_b32_e32 v200, v202
	v_mul_f32_e32 v172, v177, v170
	v_mov_b32_e32 v201, v193
	v_mul_f32_e32 v154, v161, v154
	v_mul_f32_e32 v160, v160, v164
	v_mul_f32_e32 v161, v159, v170
	v_mul_f32_e32 v164, v158, v172
	v_pk_mul_f32 v[158:159], v[200:201], v[202:203]
	v_cndmask_b32_e64 v170, 1.0, v202, s[38:39]
	v_mul_f32_e32 v170, v170, v159
	v_mul_f32_e32 v169, v169, v170
	v_mul_f32_e32 v168, v168, v169
	v_mul_f32_e32 v172, v173, v168
	v_mul_f32_e32 v156, v156, v169
	v_mul_f32_e32 v168, v147, v168
	v_mul_f32_e32 v169, v146, v172
	v_pk_mul_f32 v[146:147], v[158:159], v[158:159] op_sel:[0,1] op_sel_hi:[1,0]
	v_mov_b32_e32 v198, v196
	v_cndmask_b32_e64 v147, 1.0, v150, s[38:39]
	v_mul_f32_e32 v147, v147, v146
	v_mul_f32_e32 v150, v167, v147
	v_mul_f32_e32 v158, v166, v150
	v_permlane32_swap_b32_e32 v196, v198
	v_mul_f32_e32 v159, v171, v158
	v_mov_b32_e32 v199, v146
	v_mul_f32_e32 v103, v103, v147
	v_mul_f32_e32 v102, v102, v150
	v_mul_f32_e32 v147, v99, v158
	v_mul_f32_e32 v150, v98, v159
	v_pk_mul_f32 v[98:99], v[196:197], v[198:199]
	v_cndmask_b32_e64 v146, 1.0, v198, s[38:39]
	v_mul_f32_e32 v146, v146, v99
	v_mul_f32_e32 v158, v163, v146
	v_mul_f32_e32 v159, v162, v158
	v_mul_f32_e32 v162, v165, v159
	v_mul_f32_e32 v95, v95, v146
	v_mul_f32_e32 v94, v94, v158
	v_mul_f32_e32 v146, v91, v159
	v_mul_f32_e32 v158, v90, v162
	v_pk_mul_f32 v[90:91], v[98:99], v[98:99] op_sel:[0,1] op_sel_hi:[1,0]
	v_mov_b32_e32 v194, v184
	v_cndmask_b32_e64 v91, 1.0, v148, s[38:39]
	v_mul_f32_e32 v91, v91, v90
	v_mul_f32_e32 v98, v153, v91
	v_permlane32_swap_b32_e32 v184, v194
	v_mul_f32_e32 v99, v152, v98
	v_mov_b32_e32 v195, v90
	v_mul_f32_e32 v148, v155, v99
	v_mul_f32_e32 v105, v105, v91
	v_mul_f32_e32 v99, v101, v99
	v_pk_mul_f32 v[90:91], v[184:185], v[194:195]
	v_cndmask_b32_e64 v101, 1.0, v194, s[38:39]
	v_mul_f32_e32 v101, v101, v91
	v_pk_mul_f32 v[90:91], v[90:91], v[90:91] op_sel:[0,1] op_sel_hi:[1,0]
	v_mul_f32_e32 v98, v104, v98
	v_cndmask_b32_e64 v91, 1.0, v108, s[38:39]
	v_mul_f32_e32 v91, v91, v90
	v_mul_f32_e32 v104, v113, v101
	v_mul_f32_e32 v97, v97, v101
	v_mul_f32_e32 v101, v111, v91
	v_mov_b32_e32 v182, v180
	v_mul_f32_e32 v112, v112, v104
	v_mul_f32_e32 v96, v96, v104
	v_mul_f32_e32 v104, v110, v101
	v_permlane32_swap_b32_e32 v180, v182
	v_mul_f32_e32 v108, v149, v104
	v_mov_b32_e32 v183, v90
	v_mul_f32_e32 v89, v89, v91
	v_mul_f32_e32 v88, v88, v101
	v_mul_f32_e32 v91, v87, v104
	v_mul_f32_e32 v101, v86, v108
	v_cndmask_b32_e64 v104, 1.0, v182, s[38:39]
	v_pk_mul_f32 v[86:87], v[180:181], v[182:183]
	v_mul_f32_e32 v113, v151, v112
	v_mul_f32_e32 v90, v104, v87
	v_mul_f32_e32 v104, v107, v90
	v_mul_f32_e32 v106, v106, v104
	v_mul_f32_e32 v107, v109, v106
	v_mul_f32_e32 v93, v93, v112
	v_mul_f32_e32 v92, v92, v113
	v_mul_f32_e32 v85, v85, v90
	v_mul_f32_e32 v84, v84, v104
	v_mul_f32_e32 v83, v83, v106
	v_mul_f32_e32 v82, v82, v107
	v_mul_f32_e32 v157, v157, v170
	v_mul_f32_e32 v100, v100, v148
	v_mul_f32_e32 v193, v86, v87
	v_cvt_pk_bf16_f32 v82, v82, v83
	v_cvt_pk_bf16_f32 v83, v84, v85
	v_cvt_pk_bf16_f32 v84, v101, v91
	v_cvt_pk_bf16_f32 v85, v88, v89
	v_cvt_pk_bf16_f32 v86, v92, v93
	v_cvt_pk_bf16_f32 v87, v96, v97
	v_cvt_pk_bf16_f32 v88, v100, v99
	v_cvt_pk_bf16_f32 v89, v98, v105
	v_cvt_pk_bf16_f32 v90, v158, v146
	v_cvt_pk_bf16_f32 v91, v94, v95
	v_cvt_pk_bf16_f32 v92, v150, v147
	v_cvt_pk_bf16_f32 v93, v102, v103
	v_cvt_pk_bf16_f32 v94, v169, v168
	v_cvt_pk_bf16_f32 v95, v156, v157
	v_cvt_pk_bf16_f32 v96, v164, v161
	v_cvt_pk_bf16_f32 v97, v160, v154
	s_nop 0
	v_permlane32_swap_b32_e32 v82, v84
	v_permlane32_swap_b32_e32 v83, v85
	v_permlane32_swap_b32_e32 v86, v88
	v_permlane32_swap_b32_e32 v87, v89
	v_permlane32_swap_b32_e32 v90, v92
	v_permlane32_swap_b32_e32 v91, v93
	v_permlane32_swap_b32_e32 v94, v96
	v_permlane32_swap_b32_e32 v95, v97
	ds_read_b64_tr_b16 v[98:99], v141 offset:0x200
	ds_read_b64_tr_b16 v[100:101], v141 offset:0xa00
	ds_read_b64_tr_b16 v[102:103], v141 offset:0x1200
	ds_read_b64_tr_b16 v[104:105], v141 offset:0x1a00
	ds_read_b64_tr_b16 v[106:107], v141 offset:0x2200
	ds_read_b64_tr_b16 v[108:109], v141 offset:0x2a00
	ds_read_b64_tr_b16 v[110:111], v141 offset:0x3200
	ds_read_b64_tr_b16 v[112:113], v141 offset:0x3a00
	s_waitcnt lgkmcnt(8)
	s_nop 0
	v_mfma_f32_32x32x16_bf16 v[66:81], v[82:85], v[236:239], v[66:81]
	v_mfma_f32_32x32x16_bf16 v[66:81], v[86:89], v[240:243], v[66:81]
	v_mfma_f32_32x32x16_bf16 v[66:81], v[90:93], v[244:247], v[66:81]
	v_mfma_f32_32x32x16_bf16 v[66:81], v[94:97], v[248:251], v[66:81]
	ds_read_b64_tr_b16 v[236:237], v141 offset:0x400
	ds_read_b64_tr_b16 v[238:239], v141 offset:0xc00
	ds_read_b64_tr_b16 v[240:241], v141 offset:0x1400
	ds_read_b64_tr_b16 v[242:243], v141 offset:0x1c00
	ds_read_b64_tr_b16 v[244:245], v141 offset:0x2400
	ds_read_b64_tr_b16 v[246:247], v141 offset:0x2c00
	ds_read_b64_tr_b16 v[248:249], v141 offset:0x3400
	ds_read_b64_tr_b16 v[250:251], v141 offset:0x3c00
	s_waitcnt lgkmcnt(8)
	v_mfma_f32_32x32x16_bf16 v[50:65], v[82:85], v[98:101], v[50:65]
	v_mfma_f32_32x32x16_bf16 v[50:65], v[86:89], v[102:105], v[50:65]
	v_mfma_f32_32x32x16_bf16 v[50:65], v[90:93], v[106:109], v[50:65]
	v_mfma_f32_32x32x16_bf16 v[50:65], v[94:97], v[110:113], v[50:65]
	ds_read_b64_tr_b16 v[98:99], v141 offset:0x600
	ds_read_b64_tr_b16 v[100:101], v141 offset:0xe00
	ds_read_b64_tr_b16 v[102:103], v141 offset:0x1600
	ds_read_b64_tr_b16 v[104:105], v141 offset:0x1e00
	ds_read_b64_tr_b16 v[106:107], v141 offset:0x2600
	ds_read_b64_tr_b16 v[108:109], v141 offset:0x2e00
	ds_read_b64_tr_b16 v[110:111], v141 offset:0x3600
	ds_read_b64_tr_b16 v[112:113], v141 offset:0x3e00
	s_waitcnt lgkmcnt(8)
	v_mfma_f32_32x32x16_bf16 v[34:49], v[82:85], v[236:239], v[34:49]
	v_mfma_f32_32x32x16_bf16 v[34:49], v[86:89], v[240:243], v[34:49]
	v_mfma_f32_32x32x16_bf16 v[34:49], v[90:93], v[244:247], v[34:49]
	v_mfma_f32_32x32x16_bf16 v[34:49], v[94:97], v[248:251], v[34:49]
	s_waitcnt lgkmcnt(0)
	v_mfma_f32_32x32x16_bf16 v[18:33], v[82:85], v[98:101], v[18:33]
	v_cmp_eq_f32_e32 vcc, 0, v193
	s_or_b64 s[0:1], vcc, s[40:41]
	v_cndmask_b32_e64 v82, 0, 1, s[0:1]
	v_cmp_ne_u32_e32 vcc, 0, v82
	s_cmp_eq_u64 vcc, exec
	s_cselect_b64 s[0:1], -1, 0
	v_mfma_f32_32x32x16_bf16 v[18:33], v[86:89], v[102:105], v[18:33]
	v_mfma_f32_32x32x16_bf16 v[18:33], v[90:93], v[106:109], v[18:33]
	v_mfma_f32_32x32x16_bf16 v[18:33], v[94:97], v[110:113], v[18:33]

.LBB0_927:
	s_sub_i32 s44, s31, 64
	s_cmp_lt_i32 s25, 0
	s_cselect_b64 s[18:19], -1, 0
	s_or_b64 s[18:19], s[18:19], s[0:1]
	s_cmp_gt_i32 s44, s33
	s_cselect_b64 s[44:45], -1, 0
	s_or_b64 s[18:19], s[18:19], s[44:45]
	s_and_b64 vcc, exec, s[18:19]
	s_cbranch_vccnz .LBB0_933
	s_add_i32 s0, s31, -1
	s_cmp_lt_i32 s0, s8
	v_add_u32_e32 v213, v145, v143
	v_xad_u32 v214, v143, 32, v145
	v_xad_u32 v215, v143, 64, v145
	ds_read_b128 v[146:149], v213 offset:49152
	ds_read_b128 v[150:153], v213 offset:57344
	ds_read_b128 v[224:227], v214 offset:49152
	ds_read_b128 v[228:231], v214 offset:57344
	ds_read_b128 v[232:235], v215 offset:49152
	s_waitcnt lgkmcnt(4)
	v_mfma_f32_32x32x16_bf16 v[82:97], v[146:149], v[4:7], 0
	ds_read_b128 v[146:149], v215 offset:57344
	v_xad_u32 v216, v143, s56, v145
	s_waitcnt lgkmcnt(4)
	v_mfma_f32_32x32x16_bf16 v[98:113], v[150:153], v[4:7], 0
	ds_read_b128 v[150:153], v216 offset:49152
	s_waitcnt lgkmcnt(4)
	v_mfma_f32_32x32x16_bf16 v[82:97], v[224:227], v[8:11], v[82:97]
	ds_read_b128 v[224:227], v216 offset:57344
	v_xad_u32 v213, v143, s90, v145
	s_waitcnt lgkmcnt(4)
	v_mfma_f32_32x32x16_bf16 v[98:113], v[228:231], v[8:11], v[98:113]
	ds_read_b128 v[228:231], v213 offset:49152
	s_waitcnt lgkmcnt(4)
	v_mfma_f32_32x32x16_bf16 v[82:97], v[232:235], v[12:15], v[82:97]
	ds_read_b128 v[232:235], v213 offset:57344
	v_xad_u32 v214, v143, s91, v145
	s_waitcnt lgkmcnt(4)
	v_mfma_f32_32x32x16_bf16 v[98:113], v[146:149], v[12:15], v[98:113]
	ds_read_b128 v[146:149], v214 offset:49152
	s_waitcnt lgkmcnt(4)
	v_mfma_f32_32x32x16_bf16 v[82:97], v[150:153], v[114:117], v[82:97]
	ds_read_b128 v[150:153], v214 offset:57344
	v_xad_u32 v215, v143, s57, v145
	s_waitcnt lgkmcnt(4)
	v_mfma_f32_32x32x16_bf16 v[98:113], v[224:227], v[114:117], v[98:113]
	ds_read_b128 v[224:227], v215 offset:49152
	s_waitcnt lgkmcnt(4)
	v_mfma_f32_32x32x16_bf16 v[82:97], v[228:231], v[118:121], v[82:97]
	ds_read_b128 v[228:231], v215 offset:57344
	v_xad_u32 v216, v143, s28, v145
	s_waitcnt lgkmcnt(4)
	v_mfma_f32_32x32x16_bf16 v[98:113], v[232:235], v[118:121], v[98:113]
	ds_read_b128 v[232:235], v216 offset:49152
	s_waitcnt lgkmcnt(4)
	v_mfma_f32_32x32x16_bf16 v[82:97], v[146:149], v[122:125], v[82:97]
	ds_read_b128 v[146:149], v216 offset:57344
	s_waitcnt lgkmcnt(4)
	v_mfma_f32_32x32x16_bf16 v[98:113], v[150:153], v[122:125], v[98:113]
	s_waitcnt lgkmcnt(3)
	v_mfma_f32_32x32x16_bf16 v[82:97], v[224:227], v[126:129], v[82:97]
	s_waitcnt lgkmcnt(2)
	v_mfma_f32_32x32x16_bf16 v[98:113], v[228:231], v[126:129], v[98:113]
	s_waitcnt lgkmcnt(1)
	v_mfma_f32_32x32x16_bf16 v[82:97], v[232:235], v[130:133], v[82:97]
	s_waitcnt lgkmcnt(0)
	v_mfma_f32_32x32x16_bf16 v[98:113], v[146:149], v[130:133], v[98:113]
	ds_read_b64_tr_b16 v[236:237], v141 offset:0x4000
	ds_read_b64_tr_b16 v[238:239], v141 offset:0x4800
	ds_read_b64_tr_b16 v[240:241], v141 offset:0x5000
	ds_read_b64_tr_b16 v[242:243], v141 offset:0x5800
	ds_read_b64_tr_b16 v[244:245], v141 offset:0x6000
	ds_read_b64_tr_b16 v[246:247], v141 offset:0x6800
	ds_read_b64_tr_b16 v[248:249], v141 offset:0x7000
	ds_read_b64_tr_b16 v[250:251], v141 offset:0x7800
	s_nop 2
	v_min_f32_e32 v213, 0x42fc0000, v82
	v_min_f32_e32 v214, 0x42fc0000, v83
	v_min_f32_e32 v215, 0x42fc0000, v98
	v_min_f32_e32 v216, 0x42fc0000, v99
	v_exp_f32_e32 v162, v213
	v_exp_f32_e32 v163, v214
	v_exp_f32_e32 v164, v215
	v_exp_f32_e32 v165, v216
	v_min_f32_e32 v217, 0x42fc0000, v84
	v_min_f32_e32 v218, 0x42fc0000, v100
	v_min_f32_e32 v219, 0x42fc0000, v85
	v_min_f32_e32 v220, 0x42fc0000, v101
	v_exp_f32_e32 v166, v217
	v_exp_f32_e32 v180, v218
	v_exp_f32_e32 v167, v219
	v_exp_f32_e32 v181, v220
	v_min_f32_e32 v213, 0x42fc0000, v86
	v_min_f32_e32 v214, 0x42fc0000, v102
	v_min_f32_e32 v215, 0x42fc0000, v87
	v_min_f32_e32 v216, 0x42fc0000, v103
	v_exp_f32_e32 v148, v213
	v_exp_f32_e32 v170, v214
	v_exp_f32_e32 v149, v215
	v_exp_f32_e32 v171, v216
	v_min_f32_e32 v217, 0x42fc0000, v88
	v_min_f32_e32 v218, 0x42fc0000, v104
	v_min_f32_e32 v219, 0x42fc0000, v89
	v_min_f32_e32 v220, 0x42fc0000, v105
	v_exp_f32_e32 v168, v217
	v_exp_f32_e32 v182, v218
	v_exp_f32_e32 v169, v219
	v_exp_f32_e32 v183, v220
	v_min_f32_e32 v213, 0x42fc0000, v90
	v_min_f32_e32 v214, 0x42fc0000, v106
	v_min_f32_e32 v215, 0x42fc0000, v91
	v_min_f32_e32 v216, 0x42fc0000, v107
	v_exp_f32_e32 v150, v213
	v_exp_f32_e32 v172, v214
	v_exp_f32_e32 v151, v215
	v_exp_f32_e32 v173, v216
	v_min_f32_e32 v217, 0x42fc0000, v92
	v_min_f32_e32 v218, 0x42fc0000, v108
	v_min_f32_e32 v219, 0x42fc0000, v93
	v_min_f32_e32 v220, 0x42fc0000, v109
	v_exp_f32_e32 v106, v217
	v_exp_f32_e32 v184, v218
	v_exp_f32_e32 v107, v219
	v_exp_f32_e32 v185, v220
	v_min_f32_e32 v213, 0x42fc0000, v94
	v_min_f32_e32 v214, 0x42fc0000, v110
	v_min_f32_e32 v215, 0x42fc0000, v95
	v_min_f32_e32 v216, 0x42fc0000, v111
	v_exp_f32_e32 v108, v213
	v_exp_f32_e32 v176, v214
	v_exp_f32_e32 v109, v215
	v_exp_f32_e32 v177, v216
	v_min_f32_e32 v217, 0x42fc0000, v96
	v_min_f32_e32 v218, 0x42fc0000, v112
	v_min_f32_e32 v219, 0x42fc0000, v97
	v_min_f32_e32 v220, 0x42fc0000, v113
	v_exp_f32_e32 v110, v217
	v_exp_f32_e32 v174, v218
	v_exp_f32_e32 v111, v219
	v_exp_f32_e32 v175, v220
	v_add_f32_e32 v83, 1.0, v164
	v_add_f32_e32 v84, 1.0, v165
	v_add_f32_e32 v85, 1.0, v180
	v_add_f32_e32 v86, 1.0, v181
	v_add_f32_e32 v87, 1.0, v170
	v_add_f32_e32 v88, 1.0, v171
	v_add_f32_e32 v89, 1.0, v182
	v_add_f32_e32 v92, 1.0, v183
	v_add_f32_e32 v93, 1.0, v172
	v_add_f32_e32 v96, 1.0, v173
	v_add_f32_e32 v97, 1.0, v184
	v_add_f32_e32 v100, 1.0, v185
	v_add_f32_e32 v101, 1.0, v176
	v_add_f32_e32 v104, 1.0, v177
	v_add_f32_e32 v112, 1.0, v174
	v_add_f32_e32 v82, 1.0, v162
	v_rcp_f32_e32 v90, v83
	v_add_f32_e32 v83, 1.0, v163
	v_rcp_f32_e32 v91, v84
	v_add_f32_e32 v84, 1.0, v166
	v_rcp_f32_e32 v94, v85
	v_add_f32_e32 v85, 1.0, v167
	v_rcp_f32_e32 v95, v86
	v_add_f32_e32 v86, 1.0, v148
	v_rcp_f32_e32 v98, v87
	v_add_f32_e32 v87, 1.0, v149
	v_rcp_f32_e32 v99, v88
	v_add_f32_e32 v88, 1.0, v168
	v_rcp_f32_e32 v102, v89
	v_add_f32_e32 v89, 1.0, v169
	v_rcp_f32_e32 v103, v92
	v_add_f32_e32 v92, 1.0, v150
	v_rcp_f32_e32 v146, v93
	v_add_f32_e32 v93, 1.0, v151
	v_rcp_f32_e32 v147, v96
	v_add_f32_e32 v96, 1.0, v106
	v_rcp_f32_e32 v156, v97
	v_add_f32_e32 v97, 1.0, v107
	v_rcp_f32_e32 v157, v100
	v_add_f32_e32 v100, 1.0, v108
	v_rcp_f32_e32 v158, v101
	v_add_f32_e32 v101, 1.0, v109
	v_rcp_f32_e32 v159, v104
	v_add_f32_e32 v104, 1.0, v110
	v_add_f32_e32 v105, 1.0, v111
	v_rcp_f32_e32 v160, v112
	v_add_f32_e32 v112, 1.0, v175
	v_rcp_f32_e32 v82, v82
	v_rcp_f32_e32 v83, v83
	v_rcp_f32_e32 v84, v84
	v_rcp_f32_e32 v85, v85
	v_rcp_f32_e32 v86, v86
	v_rcp_f32_e32 v87, v87
	v_rcp_f32_e32 v88, v88
	v_rcp_f32_e32 v89, v89
	v_rcp_f32_e32 v92, v92
	v_rcp_f32_e32 v93, v93
	v_rcp_f32_e32 v96, v96
	v_rcp_f32_e32 v97, v97
	v_rcp_f32_e32 v100, v100
	v_rcp_f32_e32 v101, v101
	v_rcp_f32_e32 v104, v104
	v_rcp_f32_e32 v105, v105
	v_rcp_f32_e32 v161, v112
	v_pk_mul_f32 v[154:155], v[108:109], v[100:101]
	v_pk_mul_f32 v[112:113], v[106:107], v[96:97]
	v_pk_mul_f32 v[152:153], v[110:111], v[104:105]
	v_pk_mul_f32 v[150:151], v[150:151], v[92:93]
	v_pk_mul_f32 v[110:111], v[168:169], v[88:89]
	v_pk_mul_f32 v[148:149], v[148:149], v[86:87]
	v_pk_mul_f32 v[106:107], v[166:167], v[84:85]
	v_pk_mul_f32 v[108:109], v[162:163], v[82:83]
	v_pk_mul_f32 v[174:175], v[174:175], v[160:161]
	v_pk_mul_f32 v[176:177], v[176:177], v[158:159]
	v_pk_mul_f32 v[168:169], v[184:185], v[156:157]
	v_pk_mul_f32 v[172:173], v[172:173], v[146:147]
	v_pk_mul_f32 v[166:167], v[182:183], v[102:103]
	v_pk_mul_f32 v[170:171], v[170:171], v[98:99]
	v_pk_mul_f32 v[162:163], v[180:181], v[94:95]
	v_pk_mul_f32 v[164:165], v[164:165], v[90:91]
	s_cbranch_scc1 .LBB0_932
	v_add_u32_e32 v180, 0x4000007b, v192
	s_brev_b32 s0, -4
	v_cmp_lt_u32_e32 vcc, s0, v180
	v_add_u32_e32 v180, 0x5b, v192
	v_cmp_gt_u32_e64 s[0:1], -2.0, v180
	v_add_u32_e32 v180, 0x7a, v192
	v_cmp_gt_u32_e64 s[44:45], -2.0, v180
	v_add_u32_e32 v180, 0x5a, v192
	v_cndmask_b32_e64 v90, v90, 0, s[0:1]
	v_cndmask_b32_e64 v164, v164, 1.0, s[0:1]
	v_cmp_gt_u32_e64 s[0:1], -2.0, v180
	v_add_u32_e32 v180, 0x79, v192
	v_cmp_gt_u32_e64 s[46:47], -2.0, v180
	v_add_u32_e32 v180, 0x59, v192
	v_cndmask_b32_e64 v91, v91, 0, s[0:1]
	v_cndmask_b32_e64 v165, v165, 1.0, s[0:1]
	v_cmp_gt_u32_e64 s[0:1], -2.0, v180
	v_add_u32_e32 v180, 0x78, v192
	v_cmp_gt_u32_e64 s[48:49], -2.0, v180
	v_add_u32_e32 v180, 0x58, v192
	v_cndmask_b32_e64 v94, v94, 0, s[0:1]
	v_cndmask_b32_e64 v162, v162, 1.0, s[0:1]
	v_cmp_gt_u32_e64 s[0:1], -2.0, v180
	v_add_u32_e32 v180, 0x73, v192
	v_cmp_gt_u32_e64 s[50:51], -2.0, v180
	v_add_u32_e32 v180, 0x53, v192
	v_cndmask_b32_e64 v95, v95, 0, s[0:1]
	v_cndmask_b32_e64 v163, v163, 1.0, s[0:1]
	v_cmp_gt_u32_e64 s[0:1], -2.0, v180
	v_add_u32_e32 v180, 0x72, v192
	v_cmp_gt_u32_e64 s[52:53], -2.0, v180
	v_add_u32_e32 v180, 0x52, v192
	v_cndmask_b32_e64 v98, v98, 0, s[0:1]
	v_cndmask_b32_e64 v170, v170, 1.0, s[0:1]
	v_cmp_gt_u32_e64 s[0:1], -2.0, v180
	v_add_u32_e32 v180, 0x71, v192
	v_cmp_gt_u32_e64 s[54:55], -2.0, v180
	v_add_u32_e32 v180, 0x51, v192
	v_cndmask_b32_e64 v99, v99, 0, s[0:1]
	v_cndmask_b32_e64 v171, v171, 1.0, s[0:1]
	v_cmp_gt_u32_e64 s[0:1], -2.0, v180
	v_add_u32_e32 v180, 0x70, v192
	s_nop 0
	v_cndmask_b32_e64 v102, v102, 0, s[0:1]
	v_cndmask_b32_e64 v166, v166, 1.0, s[0:1]
	v_cmp_gt_u32_e64 s[0:1], -2.0, v180
	v_add_u32_e32 v180, 0x50, v192
	v_cmp_gt_u32_e64 s[58:59], -2.0, v180
	v_add_u32_e32 v180, 0x6b, v192
	s_nop 0
	v_cndmask_b32_e64 v103, v103, 0, s[58:59]
	v_cndmask_b32_e64 v167, v167, 1.0, s[58:59]
	v_cmp_gt_u32_e64 s[58:59], -2.0, v180
	v_add_u32_e32 v180, 0x4b, v192
	v_cmp_gt_u32_e64 s[60:61], -2.0, v180
	v_add_u32_e32 v180, 0x6a, v192
	s_nop 0
	v_cndmask_b32_e64 v146, v146, 0, s[60:61]
	v_cndmask_b32_e64 v172, v172, 1.0, s[60:61]
	v_cmp_gt_u32_e64 s[60:61], -2.0, v180
	v_add_u32_e32 v180, 0x4a, v192
	v_cmp_gt_u32_e64 s[62:63], -2.0, v180
	v_add_u32_e32 v180, 0x69, v192
	s_nop 0
	v_cndmask_b32_e64 v147, v147, 0, s[62:63]
	v_cndmask_b32_e64 v173, v173, 1.0, s[62:63]
	v_cmp_gt_u32_e64 s[62:63], -2.0, v180
	v_add_u32_e32 v180, 0x49, v192
	v_cmp_gt_u32_e64 s[64:65], -2.0, v180
	v_add_u32_e32 v180, 0x68, v192
	s_nop 0
	v_cndmask_b32_e64 v156, v156, 0, s[64:65]
	v_cndmask_b32_e64 v168, v168, 1.0, s[64:65]
	v_cmp_gt_u32_e64 s[64:65], -2.0, v180
	v_add_u32_e32 v180, 0x48, v192
	v_cmp_gt_u32_e64 s[66:67], -2.0, v180
	v_add_u32_e32 v180, 0x63, v192
	s_nop 0
	v_cndmask_b32_e64 v157, v157, 0, s[66:67]
	v_cndmask_b32_e64 v169, v169, 1.0, s[66:67]
	v_cmp_gt_u32_e64 s[66:67], -2.0, v180
	v_add_u32_e32 v180, 0x43, v192
	v_cmp_gt_u32_e64 s[68:69], -2.0, v180
	v_add_u32_e32 v180, 0x62, v192
	s_nop 0
	v_cndmask_b32_e64 v158, v158, 0, s[68:69]
	v_cndmask_b32_e64 v176, v176, 1.0, s[68:69]
	v_cmp_gt_u32_e64 s[68:69], -2.0, v180
	v_add_u32_e32 v180, 0x42, v192
	v_cmp_gt_u32_e64 s[70:71], -2.0, v180
	v_add_u32_e32 v180, 0x61, v192
	s_nop 0
	v_cndmask_b32_e64 v159, v159, 0, s[70:71]
	v_cndmask_b32_e64 v177, v177, 1.0, s[70:71]
	v_cmp_gt_u32_e64 s[70:71], -2.0, v180
	v_add_u32_e32 v180, 0x41, v192
	v_cmp_gt_u32_e64 s[72:73], -2.0, v180
	v_add_u32_e32 v180, 0x60, v192
	s_nop 0
	v_cndmask_b32_e64 v160, v160, 0, s[72:73]
	v_cndmask_b32_e64 v174, v174, 1.0, s[72:73]
	v_cmp_gt_u32_e64 s[72:73], -2.0, v180
	v_add_u32_e32 v180, 64, v192
	v_cmp_gt_u32_e64 s[76:77], -2.0, v180
	s_and_saveexec_b64 s[18:19], s[76:77]
	s_mov_b32 s76, 1.0
	v_mov_b32_e32 v175, s76
	v_mov_b32_e32 v161, 0
	s_or_b64 exec, exec, s[18:19]
	v_cndmask_b32_e64 v82, v82, 0, vcc
	v_cndmask_b32_e64 v108, v108, 1.0, vcc
	v_cndmask_b32_e64 v83, v83, 0, s[44:45]
	v_cndmask_b32_e64 v109, v109, 1.0, s[44:45]
	v_cndmask_b32_e64 v84, v84, 0, s[46:47]
	v_cndmask_b32_e64 v106, v106, 1.0, s[46:47]
	v_cndmask_b32_e64 v85, v85, 0, s[48:49]
	v_cndmask_b32_e64 v107, v107, 1.0, s[48:49]
	v_cndmask_b32_e64 v86, v86, 0, s[50:51]
	v_cndmask_b32_e64 v148, v148, 1.0, s[50:51]
	v_cndmask_b32_e64 v87, v87, 0, s[52:53]
	v_cndmask_b32_e64 v149, v149, 1.0, s[52:53]
	v_cndmask_b32_e64 v88, v88, 0, s[54:55]
	v_cndmask_b32_e64 v110, v110, 1.0, s[54:55]
	v_cndmask_b32_e64 v89, v89, 0, s[0:1]
	v_cndmask_b32_e64 v111, v111, 1.0, s[0:1]
	v_cndmask_b32_e64 v92, v92, 0, s[58:59]
	v_cndmask_b32_e64 v150, v150, 1.0, s[58:59]
	v_cndmask_b32_e64 v93, v93, 0, s[60:61]
	v_cndmask_b32_e64 v151, v151, 1.0, s[60:61]
	v_cndmask_b32_e64 v96, v96, 0, s[62:63]
	v_cndmask_b32_e64 v112, v112, 1.0, s[62:63]
	v_cndmask_b32_e64 v97, v97, 0, s[64:65]
	v_cndmask_b32_e64 v113, v113, 1.0, s[64:65]
	v_cndmask_b32_e64 v100, v100, 0, s[66:67]
	v_cndmask_b32_e64 v154, v154, 1.0, s[66:67]
	v_cndmask_b32_e64 v101, v101, 0, s[68:69]
	v_cndmask_b32_e64 v155, v155, 1.0, s[68:69]
	v_cndmask_b32_e64 v104, v104, 0, s[70:71]
	v_cndmask_b32_e64 v152, v152, 1.0, s[70:71]
	v_cndmask_b32_e64 v105, v105, 0, s[72:73]
	v_cndmask_b32_e64 v153, v153, 1.0, s[72:73]
	v_readlane_b32 s48, v254, 46
.LBB0_932:
	v_mov_b32_e32 v184, v149
	v_mov_b32_e32 v185, v110
	v_mov_b32_e32 v194, v148
	v_mov_b32_e32 v195, v111
	v_pk_mul_f32 v[184:185], v[184:185], v[194:195]
	v_mov_b32_e32 v180, v109
	v_mov_b32_e32 v181, v106
	v_mov_b32_e32 v182, v108
	v_mov_b32_e32 v183, v107
	v_pk_mul_f32 v[184:185], v[184:185], v[184:185] op_sel:[0,1] op_sel_hi:[1,0]
	v_pk_mul_f32 v[180:181], v[180:181], v[182:183]
	v_mov_b32_e32 v108, v184
	v_mov_b32_e32 v196, v155
	v_mov_b32_e32 v197, v152
	v_mov_b32_e32 v198, v154
	v_mov_b32_e32 v199, v153
	v_pk_mul_f32 v[180:181], v[180:181], v[180:181] op_sel:[0,1] op_sel_hi:[1,0]
	v_permlane32_swap_b32_e32 v184, v108
	v_pk_mul_f32 v[196:197], v[196:197], v[198:199]
	v_mul_f32_e32 v181, v184, v108
	v_mov_b32_e32 v184, v151
	v_mov_b32_e32 v185, v112
	v_mov_b32_e32 v194, v150
	v_mov_b32_e32 v195, v113
	v_pk_mul_f32 v[196:197], v[196:197], v[196:197] op_sel:[0,1] op_sel_hi:[1,0]
	v_pk_mul_f32 v[184:185], v[184:185], v[194:195]
	v_mov_b32_e32 v148, v196
	v_mov_b32_e32 v200, v171
	v_mov_b32_e32 v201, v166
	v_mov_b32_e32 v202, v170
	v_mov_b32_e32 v203, v167
	v_pk_mul_f32 v[184:185], v[184:185], v[184:185] op_sel:[0,1] op_sel_hi:[1,0]
	v_permlane32_swap_b32_e32 v196, v148
	v_pk_mul_f32 v[200:201], v[200:201], v[202:203]
	v_mov_b32_e32 v204, v177
	v_mov_b32_e32 v205, v174
	v_mov_b32_e32 v206, v176
	v_mov_b32_e32 v207, v175
	v_mul_f32_e32 v185, v196, v148
	v_mov_b32_e32 v196, v165
	v_mov_b32_e32 v197, v162
	v_mov_b32_e32 v198, v164
	v_mov_b32_e32 v199, v163
	v_pk_mul_f32 v[200:201], v[200:201], v[200:201] op_sel:[0,1] op_sel_hi:[1,0]
	v_pk_mul_f32 v[204:205], v[204:205], v[206:207]
	v_pk_mul_f32 v[196:197], v[196:197], v[198:199]
	v_mov_b32_e32 v150, v200
	v_pk_mul_f32 v[204:205], v[204:205], v[204:205] op_sel:[0,1] op_sel_hi:[1,0]
	v_pk_mul_f32 v[196:197], v[196:197], v[196:197] op_sel:[0,1] op_sel_hi:[1,0]
	v_permlane32_swap_b32_e32 v200, v150
	v_mov_b32_e32 v154, v204
	v_mul_f32_e32 v197, v200, v150
	v_mov_b32_e32 v200, v173
	v_mov_b32_e32 v201, v168
	v_mov_b32_e32 v202, v172
	v_mov_b32_e32 v203, v169
	v_permlane32_swap_b32_e32 v204, v154
	v_pk_mul_f32 v[200:201], v[200:201], v[202:203]
	v_mul_f32_e32 v203, v204, v154
	v_cndmask_b32_e64 v154, 1.0, v154, s[38:39]
	v_mul_f32_e32 v154, v193, v154
	v_pk_mul_f32 v[200:201], v[200:201], v[200:201] op_sel:[0,1] op_sel_hi:[1,0]
	v_mul_f32_e32 v164, v175, v154
	v_mov_b32_e32 v202, v200
	v_mul_f32_e32 v170, v174, v164
	s_nop 0
	v_permlane32_swap_b32_e32 v200, v202
	v_mul_f32_e32 v172, v177, v170
	v_mov_b32_e32 v201, v193
	v_mul_f32_e32 v154, v161, v154
	v_mul_f32_e32 v160, v160, v164
	v_mul_f32_e32 v161, v159, v170
	v_mul_f32_e32 v164, v158, v172
	v_pk_mul_f32 v[158:159], v[200:201], v[202:203]
	v_cndmask_b32_e64 v170, 1.0, v202, s[38:39]
	v_mul_f32_e32 v170, v170, v159
	v_mul_f32_e32 v169, v169, v170
	v_mul_f32_e32 v168, v168, v169
	v_mul_f32_e32 v172, v173, v168
	v_mul_f32_e32 v156, v156, v169
	v_mul_f32_e32 v168, v147, v168
	v_mul_f32_e32 v169, v146, v172
	v_pk_mul_f32 v[146:147], v[158:159], v[158:159] op_sel:[0,1] op_sel_hi:[1,0]
	v_mov_b32_e32 v198, v196
	v_cndmask_b32_e64 v147, 1.0, v150, s[38:39]
	v_mul_f32_e32 v147, v147, v146
	v_mul_f32_e32 v150, v167, v147
	v_mul_f32_e32 v158, v166, v150
	v_permlane32_swap_b32_e32 v196, v198
	v_mul_f32_e32 v159, v171, v158
	v_mov_b32_e32 v199, v146
	v_mul_f32_e32 v103, v103, v147
	v_mul_f32_e32 v102, v102, v150
	v_mul_f32_e32 v147, v99, v158
	v_mul_f32_e32 v150, v98, v159
	v_pk_mul_f32 v[98:99], v[196:197], v[198:199]
	v_cndmask_b32_e64 v146, 1.0, v198, s[38:39]
	v_mul_f32_e32 v146, v146, v99
	v_mul_f32_e32 v158, v163, v146
	v_mul_f32_e32 v159, v162, v158
	v_mul_f32_e32 v162, v165, v159
	v_mul_f32_e32 v95, v95, v146
	v_mul_f32_e32 v94, v94, v158
	v_mul_f32_e32 v146, v91, v159
	v_mul_f32_e32 v158, v90, v162
	v_pk_mul_f32 v[90:91], v[98:99], v[98:99] op_sel:[0,1] op_sel_hi:[1,0]
	v_mov_b32_e32 v194, v184
	v_cndmask_b32_e64 v91, 1.0, v148, s[38:39]
	v_mul_f32_e32 v91, v91, v90
	v_mul_f32_e32 v98, v153, v91
	v_permlane32_swap_b32_e32 v184, v194
	v_mul_f32_e32 v99, v152, v98
	v_mov_b32_e32 v195, v90
	v_mul_f32_e32 v148, v155, v99
	v_mul_f32_e32 v105, v105, v91
	v_mul_f32_e32 v99, v101, v99
	v_pk_mul_f32 v[90:91], v[184:185], v[194:195]
	v_cndmask_b32_e64 v101, 1.0, v194, s[38:39]
	v_mul_f32_e32 v101, v101, v91
	v_pk_mul_f32 v[90:91], v[90:91], v[90:91] op_sel:[0,1] op_sel_hi:[1,0]
	v_mul_f32_e32 v98, v104, v98
	v_cndmask_b32_e64 v91, 1.0, v108, s[38:39]
	v_mul_f32_e32 v91, v91, v90
	v_mul_f32_e32 v104, v113, v101
	v_mul_f32_e32 v97, v97, v101
	v_mul_f32_e32 v101, v111, v91
	v_mov_b32_e32 v182, v180
	v_mul_f32_e32 v112, v112, v104
	v_mul_f32_e32 v96, v96, v104
	v_mul_f32_e32 v104, v110, v101
	v_permlane32_swap_b32_e32 v180, v182
	v_mul_f32_e32 v108, v149, v104
	v_mov_b32_e32 v183, v90
	v_mul_f32_e32 v89, v89, v91
	v_mul_f32_e32 v88, v88, v101
	v_mul_f32_e32 v91, v87, v104
	v_mul_f32_e32 v101, v86, v108
	v_cndmask_b32_e64 v104, 1.0, v182, s[38:39]
	v_pk_mul_f32 v[86:87], v[180:181], v[182:183]
	v_mul_f32_e32 v113, v151, v112
	v_mul_f32_e32 v90, v104, v87
	v_mul_f32_e32 v104, v107, v90
	v_mul_f32_e32 v106, v106, v104
	v_mul_f32_e32 v107, v109, v106
	v_mul_f32_e32 v93, v93, v112
	v_mul_f32_e32 v92, v92, v113
	v_mul_f32_e32 v85, v85, v90
	v_mul_f32_e32 v84, v84, v104
	v_mul_f32_e32 v83, v83, v106
	v_mul_f32_e32 v82, v82, v107
	v_mul_f32_e32 v157, v157, v170
	v_mul_f32_e32 v100, v100, v148
	v_mul_f32_e32 v193, v86, v87
	v_cvt_pk_bf16_f32 v82, v82, v83
	v_cvt_pk_bf16_f32 v83, v84, v85
	v_cvt_pk_bf16_f32 v84, v101, v91
	v_cvt_pk_bf16_f32 v85, v88, v89
	v_cvt_pk_bf16_f32 v86, v92, v93
	v_cvt_pk_bf16_f32 v87, v96, v97
	v_cvt_pk_bf16_f32 v88, v100, v99
	v_cvt_pk_bf16_f32 v89, v98, v105
	v_cvt_pk_bf16_f32 v90, v158, v146
	v_cvt_pk_bf16_f32 v91, v94, v95
	v_cvt_pk_bf16_f32 v92, v150, v147
	v_cvt_pk_bf16_f32 v93, v102, v103
	v_cvt_pk_bf16_f32 v94, v169, v168
	v_cvt_pk_bf16_f32 v95, v156, v157
	v_cvt_pk_bf16_f32 v96, v164, v161
	v_cvt_pk_bf16_f32 v97, v160, v154
	s_nop 0
	v_permlane32_swap_b32_e32 v82, v84
	v_permlane32_swap_b32_e32 v83, v85
	v_permlane32_swap_b32_e32 v86, v88
	v_permlane32_swap_b32_e32 v87, v89
	v_permlane32_swap_b32_e32 v90, v92
	v_permlane32_swap_b32_e32 v91, v93
	v_permlane32_swap_b32_e32 v94, v96
	v_permlane32_swap_b32_e32 v95, v97
	ds_read_b64_tr_b16 v[98:99], v141 offset:0x4200
	ds_read_b64_tr_b16 v[100:101], v141 offset:0x4a00
	ds_read_b64_tr_b16 v[102:103], v141 offset:0x5200
	ds_read_b64_tr_b16 v[104:105], v141 offset:0x5a00
	ds_read_b64_tr_b16 v[106:107], v141 offset:0x6200
	ds_read_b64_tr_b16 v[108:109], v141 offset:0x6a00
	ds_read_b64_tr_b16 v[110:111], v141 offset:0x7200
	ds_read_b64_tr_b16 v[112:113], v141 offset:0x7a00
	s_waitcnt lgkmcnt(8)
	s_nop 0
	v_mfma_f32_32x32x16_bf16 v[66:81], v[82:85], v[236:239], v[66:81]
	v_mfma_f32_32x32x16_bf16 v[66:81], v[86:89], v[240:243], v[66:81]
	v_mfma_f32_32x32x16_bf16 v[66:81], v[90:93], v[244:247], v[66:81]
	v_mfma_f32_32x32x16_bf16 v[66:81], v[94:97], v[248:251], v[66:81]
	ds_read_b64_tr_b16 v[236:237], v141 offset:0x4400
	ds_read_b64_tr_b16 v[238:239], v141 offset:0x4c00
	ds_read_b64_tr_b16 v[240:241], v141 offset:0x5400
	ds_read_b64_tr_b16 v[242:243], v141 offset:0x5c00
	ds_read_b64_tr_b16 v[244:245], v141 offset:0x6400
	ds_read_b64_tr_b16 v[246:247], v141 offset:0x6c00
	ds_read_b64_tr_b16 v[248:249], v141 offset:0x7400
	ds_read_b64_tr_b16 v[250:251], v141 offset:0x7c00
	s_waitcnt lgkmcnt(8)
	v_mfma_f32_32x32x16_bf16 v[50:65], v[82:85], v[98:101], v[50:65]
	v_mfma_f32_32x32x16_bf16 v[50:65], v[86:89], v[102:105], v[50:65]
	v_mfma_f32_32x32x16_bf16 v[50:65], v[90:93], v[106:109], v[50:65]
	v_mfma_f32_32x32x16_bf16 v[50:65], v[94:97], v[110:113], v[50:65]
	ds_read_b64_tr_b16 v[98:99], v141 offset:0x4600
	ds_read_b64_tr_b16 v[100:101], v141 offset:0x4e00
	ds_read_b64_tr_b16 v[102:103], v141 offset:0x5600
	ds_read_b64_tr_b16 v[104:105], v141 offset:0x5e00
	ds_read_b64_tr_b16 v[106:107], v141 offset:0x6600
	ds_read_b64_tr_b16 v[108:109], v141 offset:0x6e00
	ds_read_b64_tr_b16 v[110:111], v141 offset:0x7600
	ds_read_b64_tr_b16 v[112:113], v141 offset:0x7e00
	s_waitcnt lgkmcnt(8)
	v_mfma_f32_32x32x16_bf16 v[34:49], v[82:85], v[236:239], v[34:49]
	v_mfma_f32_32x32x16_bf16 v[34:49], v[86:89], v[240:243], v[34:49]
	v_mfma_f32_32x32x16_bf16 v[34:49], v[90:93], v[244:247], v[34:49]
	v_mfma_f32_32x32x16_bf16 v[34:49], v[94:97], v[248:251], v[34:49]
	s_waitcnt lgkmcnt(0)
	v_mfma_f32_32x32x16_bf16 v[18:33], v[82:85], v[98:101], v[18:33]
	v_cmp_eq_f32_e32 vcc, 0, v193
	s_or_b64 s[0:1], vcc, s[40:41]
	v_cndmask_b32_e64 v82, 0, 1, s[0:1]
	v_cmp_ne_u32_e32 vcc, 0, v82
	s_cmp_eq_u64 vcc, exec
	s_cselect_b64 s[0:1], -1, 0
	v_mfma_f32_32x32x16_bf16 v[18:33], v[86:89], v[102:105], v[18:33]
	v_mfma_f32_32x32x16_bf16 v[18:33], v[90:93], v[106:109], v[18:33]
	v_mfma_f32_32x32x16_bf16 v[18:33], v[94:97], v[110:113], v[18:33]
